# scan L2 touch extended: sibling value slices (which share 128-B lines) split the touch of their v / gate rows two chunks ahead (even slice touches v, odd slice touches gate), plus SC/DEC lines
# speedup vs baseline: 1.0035x; 1.0031x over previous
.LBB0_250:
	v_mov_b32_e32 v4, v3
	v_mov_b32_e32 v5, v3
	v_mov_b32_e32 v100, v3
	v_mov_b32_e32 v101, v3
	v_lshl_add_u64 v[146:147], v[2:3], 1, s[56:57]
	s_lshl_b32 s22, s25, 9
	s_lshl_b32 s23, s60, 6
	v_mov_b32_e32 v2, v3
	v_mov_b32_e32 v98, v3
	v_mov_b32_e32 v99, v3
	v_mov_b64_e32 v[132:133], v[100:101]
	v_mov_b64_e32 v[104:105], v[100:101]
	v_mov_b64_e32 v[136:137], v[100:101]
	v_mov_b64_e32 v[108:109], v[100:101]
	v_mov_b64_e32 v[120:121], v[100:101]
	v_mov_b64_e32 v[112:113], v[100:101]
	v_mov_b64_e32 v[116:117], v[100:101]
	v_mov_b64_e32 v[80:81], v[4:5]
	s_add_i32 s22, s22, s0
	v_lshl_add_u32 v165, s60, 7, v207
	v_lshl_add_u32 v166, s60, 8, v206
	s_mov_b32 s74, 0
	s_lshl_b32 s23, s23, 2
	v_mov_b64_e32 v[130:131], v[98:99]
	v_mov_b64_e32 v[102:103], v[98:99]
	v_mov_b64_e32 v[134:135], v[98:99]
	v_mov_b64_e32 v[106:107], v[98:99]
	v_mov_b64_e32 v[118:119], v[98:99]
	v_mov_b64_e32 v[110:111], v[98:99]
	v_mov_b64_e32 v[114:115], v[98:99]
	v_mov_b64_e32 v[78:79], v[2:3]
	v_and_b32_e32 v235, 63, v151
	s_lshr_b32 s98, s92, 3
	s_and_b32 s98, s98, 15
	s_lshl_b32 s98, s98, 2
	v_bfe_u32 v244, v235, 3, 2
	s_add_i32 s99, s98, s94
	v_add_u32_e32 v244, s99, v244
	s_movk_i32 s99, 0x6080
	v_mul_lo_u32 v244, v244, s99
	v_and_b32_e32 v245, 3, v235
	v_lshlrev_b32_e32 v245, 7, v245
	v_bfe_u32 v246, v235, 2, 1
	v_mul_u32_u24_e32 v246, 2048, v246
	s_lshl_b32 s99, s0, 9
	v_add3_u32 v244, v244, v245, v246
	v_add_u32_e32 v244, s99, v244
	v_mov_b32_e32 v245, 0
	v_lshl_add_u64 v[236:237], v[244:245], 0, s[56:57]
	v_mov_b32_e32 v238, 0x182000
	v_mul_u32_u24_e32 v242, 0x6080, v235
	s_lshl_b32 s99, s0, 10
	s_lshl_b32 s100, s98, 4
	s_add_i32 s99, s99, s100
	v_add_u32_e32 v242, s99, v242
	v_add_u32_e32 v243, 16384, v242
	v_add_u32_e32 v242, 4096, v242
	s_lshl_b32 s99, s22, 13
	s_lshl_b32 s100, s98, 7
	s_add_i32 s99, s99, s100
	v_and_b32_e32 v244, 3, v235
	v_lshlrev_b32_e32 v244, 7, v244
	v_add_u32_e32 v244, s99, v244
	v_lshl_add_u64 v[240:241], v[244:245], 0, s[58:59]
	v_cmp_lt_u32_e32 vcc, 31, v235
	s_nop 1
	v_cndmask_b32_e32 v236, v236, v240, vcc
	v_cndmask_b32_e32 v237, v237, v241, vcc
	v_mov_b32_e32 v246, 0x8000
	v_cndmask_b32_e32 v238, v238, v246, vcc
	s_lshl_b32 s99, s22, 10
	v_and_b32_e32 v244, 7, v235
	v_lshlrev_b32_e32 v244, 7, v244
	v_add_u32_e32 v244, s99, v244
	v_lshl_add_u64 v[240:241], v[244:245], 0, s[72:73]
	v_cmp_lt_u32_e32 vcc, 35, v235
	s_nop 1
	v_cndmask_b32_e32 v236, v236, v240, vcc
	v_cndmask_b32_e32 v237, v237, v241, vcc
	v_mov_b32_e32 v246, 0x1000
	v_cndmask_b32_e32 v238, v238, v246, vcc
	s_lshr_b32 s98, s92, 3
	s_and_b32 s98, s98, 15
	s_bitcmp1_b32 s98, 0
	s_cbranch_scc0 .Lpf_even_p3
	v_mov_b32_e32 v242, v243
.Lpf_even_p3:
	s_branch .LBB0_252
.LBB0_251:
	s_add_i32 s26, s74, 3
	s_cmpk_lt_u32 s74, 0x7d
	s_mov_b32 s74, s26
	s_cbranch_scc0 .LBB0_265
.LBB0_252:
	s_min_u32 s75, s74, 0x7d
	s_add_i32 s75, s75, 2
	s_lshl_b32 s26, s75, 6
	s_add_i32 s26, s26, s94
	v_mad_i64_i32 v[4:5], s[26:27], s26, v230, v[146:147]
	s_waitcnt vmcnt(8)
	v_add_co_u32_e32 v82, vcc, s81, v4
	s_waitcnt lgkmcnt(0)
	s_barrier
	s_nop 0
	v_addc_co_u32_e32 v83, vcc, 0, v5, vcc
	global_load_dwordx4 v[142:145], v[4:5], off
	global_load_dwordx4 v[138:141], v[82:83], off offset:256
	v_add_co_u32_e32 v82, vcc, s82, v4
	s_nop 1
	v_addc_co_u32_e32 v83, vcc, 0, v5, vcc
	v_add_co_u32_e32 v84, vcc, s83, v4
	s_nop 1
	v_addc_co_u32_e32 v85, vcc, 0, v5, vcc
	global_load_dwordx4 v[126:129], v[82:83], off offset:512
	global_load_dwordx4 v[122:125], v[84:85], off offset:768
	v_add_co_u32_e32 v82, vcc, s84, v4
	s_nop 1
	v_addc_co_u32_e32 v83, vcc, 0, v5, vcc
	v_add_co_u32_e32 v84, vcc, 0x3c000, v4
	s_nop 1
	v_addc_co_u32_e32 v85, vcc, 0, v5, vcc
	global_load_dwordx4 v[94:97], v[82:83], off offset:1024
	global_load_dwordx4 v[90:93], v[84:85], off offset:1280
	v_add_co_u32_e32 v82, vcc, 0x48000, v4
	s_nop 1
	v_addc_co_u32_e32 v83, vcc, 0, v5, vcc
	v_add_co_u32_e32 v4, vcc, 0x54000, v4
	s_nop 1
	v_addc_co_u32_e32 v5, vcc, 0, v5, vcc
	global_load_dwordx4 v[86:89], v[82:83], off offset:1536
	s_nop 0
	global_load_dwordx4 v[82:85], v[4:5], off offset:1792
	s_and_b64 vcc, exec, s[16:17]
	s_cbranch_vccnz .LBB0_254
	s_lshl_b32 s26, s75, 2
	s_add_i32 s26, s26, s22
	s_ashr_i32 s27, s26, 31
	s_lshl_b64 s[26:27], s[26:27], 10
	v_lshl_add_u64 v[4:5], v[158:159], 0, s[26:27]
	global_load_dwordx4 v[78:81], v[4:5], off
	s_min_u32 s99, s74, 0x7d
	s_add_i32 s99, s99, 4
	s_min_u32 s99, s99, 0x7f
	v_mad_u64_u32 v[240:241], vcc, v238, s99, v[236:237]
	global_load_dword v239, v[240:241], off
	s_lshl_b32 s99, s99, 6
	s_add_i32 s99, s99, s94
	s_mul_hi_u32 s101, s99, 0x6080
	s_mul_i32 s100, s99, 0x6080
	s_add_u32 s100, s100, s56
	s_addc_u32 s101, s101, s57
	global_load_dword v239, v242, s[100:101]

.LBB0_256:
	s_min_u32 s97, s74, 0x7c
	s_add_i32 s97, s97, 3
	s_lshl_b32 s26, s97, 6
	s_add_i32 s26, s26, s94
	v_mad_i64_i32 v[18:19], s[26:27], s26, v230, v[146:147]
	v_add_co_u32_e32 v20, vcc, 0xc000, v18
	s_waitcnt lgkmcnt(0)
	s_barrier
	s_nop 0
	v_addc_co_u32_e32 v21, vcc, 0, v19, vcc
	global_load_dwordx4 v[50:53], v[18:19], off
	global_load_dwordx4 v[54:57], v[20:21], off offset:256
	v_add_co_u32_e32 v20, vcc, 0x18000, v18
	s_nop 1
	v_addc_co_u32_e32 v21, vcc, 0, v19, vcc
	v_add_co_u32_e32 v22, vcc, 0x24000, v18
	s_nop 1
	v_addc_co_u32_e32 v23, vcc, 0, v19, vcc
	global_load_dwordx4 v[38:41], v[20:21], off offset:512
	global_load_dwordx4 v[42:45], v[22:23], off offset:768
	v_add_co_u32_e32 v20, vcc, 0x30000, v18
	s_nop 1
	v_addc_co_u32_e32 v21, vcc, 0, v19, vcc
	v_add_co_u32_e32 v22, vcc, 0x3c000, v18
	s_nop 1
	v_addc_co_u32_e32 v23, vcc, 0, v19, vcc
	global_load_dwordx4 v[26:29], v[20:21], off offset:1024
	global_load_dwordx4 v[30:33], v[22:23], off offset:1280
	v_add_co_u32_e32 v20, vcc, 0x48000, v18
	s_nop 1
	v_addc_co_u32_e32 v21, vcc, 0, v19, vcc
	v_add_co_u32_e32 v22, vcc, 0x54000, v18
	s_nop 1
	v_addc_co_u32_e32 v23, vcc, 0, v19, vcc
	global_load_dwordx4 v[18:21], v[20:21], off offset:1536
	s_nop 0
	global_load_dwordx4 v[22:25], v[22:23], off offset:1792
	s_and_b64 vcc, exec, s[16:17]
	s_cbranch_vccnz .LBB0_258
	s_lshl_b32 s26, s97, 2
	s_add_i32 s26, s26, s22
	s_ashr_i32 s27, s26, 31
	s_lshl_b64 s[26:27], s[26:27], 10
	v_lshl_add_u64 v[6:7], v[158:159], 0, s[26:27]
	global_load_dwordx4 v[6:9], v[6:7], off
	s_min_u32 s99, s74, 0x7c
	s_add_i32 s99, s99, 5
	s_min_u32 s99, s99, 0x7f
	v_mad_u64_u32 v[240:241], vcc, v238, s99, v[236:237]
	global_load_dword v239, v[240:241], off
	s_lshl_b32 s99, s99, 6
	s_add_i32 s99, s99, s94
	s_mul_hi_u32 s101, s99, 0x6080
	s_mul_i32 s100, s99, 0x6080
	s_add_u32 s100, s100, s56
	s_addc_u32 s101, s101, s57
	global_load_dword v239, v242, s[100:101]

.LBB0_260:
	s_cmpk_gt_u32 s74, 0x7d
	s_cbranch_scc1 .LBB0_251
	s_min_u32 s86, s74, 0x7b
	s_add_i32 s86, s86, 4
	s_lshl_b32 s26, s86, 6
	s_add_i32 s26, s26, s94
	v_mad_i64_i32 v[70:71], s[26:27], s26, v230, v[146:147]
	v_add_co_u32_e32 v14, vcc, 0xc000, v70
	s_waitcnt lgkmcnt(0)
	s_barrier
	s_nop 0
	v_addc_co_u32_e32 v15, vcc, 0, v71, vcc
	v_add_co_u32_e32 v34, vcc, 0x18000, v70
	global_load_dwordx4 v[10:13], v[70:71], off
	s_nop 0
	global_load_dwordx4 v[14:17], v[14:15], off offset:256
	v_addc_co_u32_e32 v35, vcc, 0, v71, vcc
	v_add_co_u32_e32 v46, vcc, 0x24000, v70
	s_nop 1
	v_addc_co_u32_e32 v47, vcc, 0, v71, vcc
	v_add_co_u32_e32 v62, vcc, 0x30000, v70
	global_load_dwordx4 v[34:37], v[34:35], off offset:512
	s_nop 0
	global_load_dwordx4 v[46:49], v[46:47], off offset:768
	v_addc_co_u32_e32 v63, vcc, 0, v71, vcc
	v_add_co_u32_e32 v66, vcc, 0x3c000, v70
	s_nop 1
	v_addc_co_u32_e32 v67, vcc, 0, v71, vcc
	v_add_co_u32_e32 v72, vcc, 0x48000, v70
	global_load_dwordx4 v[62:65], v[62:63], off offset:1024
	s_nop 0
	global_load_dwordx4 v[66:69], v[66:67], off offset:1280
	v_addc_co_u32_e32 v73, vcc, 0, v71, vcc
	v_add_co_u32_e32 v74, vcc, 0x54000, v70
	s_nop 1
	v_addc_co_u32_e32 v75, vcc, 0, v71, vcc
	global_load_dwordx4 v[70:73], v[72:73], off offset:1536
	s_nop 0
	global_load_dwordx4 v[74:77], v[74:75], off offset:1792
	s_and_b64 vcc, exec, s[16:17]
	s_cbranch_vccnz .LBB0_263
	s_lshl_b32 s26, s86, 2
	s_add_i32 s26, s26, s22
	s_ashr_i32 s27, s26, 31
	s_lshl_b64 s[26:27], s[26:27], 10
	v_lshl_add_u64 v[58:59], v[158:159], 0, s[26:27]
	global_load_dwordx4 v[58:61], v[58:59], off
	s_min_u32 s99, s74, 0x7b
	s_add_i32 s99, s99, 6
	s_min_u32 s99, s99, 0x7f
	v_mad_u64_u32 v[240:241], vcc, v238, s99, v[236:237]
	global_load_dword v239, v[240:241], off
	s_lshl_b32 s99, s99, 6
	s_add_i32 s99, s99, s94
	s_mul_hi_u32 s101, s99, 0x6080
	s_mul_i32 s100, s99, 0x6080
	s_add_u32 s100, s100, s56
	s_addc_u32 s101, s101, s57
	global_load_dword v239, v242, s[100:101]

.LBB0_692:
	v_mov_b32_e32 v2, v1
	v_mov_b32_e32 v3, v1
	v_mov_b32_e32 v94, v1
	v_mov_b32_e32 v95, v1
	v_lshl_add_u64 v[144:145], v[0:1], 1, s[56:57]
	s_lshl_b32 s10, s13, 10
	s_lshl_b32 s11, s14, 6
	v_mov_b32_e32 v0, v1
	v_mov_b32_e32 v92, v1
	v_mov_b32_e32 v93, v1
	v_mov_b64_e32 v[130:131], v[94:95]
	v_mov_b64_e32 v[102:103], v[94:95]
	v_mov_b64_e32 v[134:135], v[94:95]
	v_mov_b64_e32 v[106:107], v[94:95]
	v_mov_b64_e32 v[118:119], v[94:95]
	v_mov_b64_e32 v[114:115], v[94:95]
	v_mov_b64_e32 v[110:111], v[94:95]
	v_mov_b64_e32 v[78:79], v[2:3]
	s_add_i32 s10, s10, s35
	v_lshl_add_u32 v149, s14, 7, v179
	v_lshl_add_u32 v150, s14, 8, v178
	s_mov_b32 s38, 0
	s_lshl_b32 s11, s11, 2
	v_mov_b64_e32 v[128:129], v[92:93]
	v_mov_b64_e32 v[100:101], v[92:93]
	v_mov_b64_e32 v[132:133], v[92:93]
	v_mov_b64_e32 v[104:105], v[92:93]
	v_mov_b64_e32 v[116:117], v[92:93]
	v_mov_b64_e32 v[112:113], v[92:93]
	v_mov_b64_e32 v[108:109], v[92:93]
	v_mov_b64_e32 v[76:77], v[0:1]
	v_and_b32_e32 v201, 63, v170
	s_bfe_u32 s98, s27, 0x40003
	s_lshl_b32 s98, s98, 2
	v_bfe_u32 v210, v201, 3, 2
	s_add_i32 s99, s98, s37
	v_add_u32_e32 v210, s99, v210
	s_movk_i32 s99, 0x6080
	v_mul_lo_u32 v210, v210, s99
	v_and_b32_e32 v211, 3, v201
	v_lshlrev_b32_e32 v211, 7, v211
	v_bfe_u32 v212, v201, 2, 1
	v_mul_u32_u24_e32 v212, 4096, v212
	s_lshl_b32 s99, s35, 9
	v_add3_u32 v210, v210, v211, v212
	v_add_u32_e32 v210, s99, v210
	v_mov_b32_e32 v211, 0
	v_lshl_add_u64 v[202:203], v[210:211], 0, s[56:57]
	v_mov_b32_e32 v204, 0x182000
	v_mul_u32_u24_e32 v208, 0x6080, v201
	s_lshl_b32 s99, s35, 10
	s_lshl_b32 s100, s98, 4
	s_add_i32 s99, s99, s100
	v_add_u32_e32 v208, s99, v208
	v_add_u32_e32 v209, 16384, v208
	v_add_u32_e32 v208, 8192, v208
	s_lshl_b32 s99, s10, 13
	s_lshl_b32 s100, s98, 7
	s_add_i32 s99, s99, s100
	v_and_b32_e32 v210, 3, v201
	v_lshlrev_b32_e32 v210, 7, v210
	v_add_u32_e32 v210, s99, v210
	v_lshl_add_u64 v[206:207], v[210:211], 0, s[58:59]
	v_cmp_lt_u32_e32 vcc, 31, v201
	s_nop 1
	v_cndmask_b32_e32 v202, v202, v206, vcc
	v_cndmask_b32_e32 v203, v203, v207, vcc
	v_mov_b32_e32 v212, 0x10000
	v_cndmask_b32_e32 v204, v204, v212, vcc
	s_lshl_b32 s99, s10, 10
	v_and_b32_e32 v210, 7, v201
	v_lshlrev_b32_e32 v210, 7, v210
	v_add_u32_e32 v210, s99, v210
	v_lshl_add_u64 v[206:207], v[210:211], 0, s[72:73]
	v_cmp_lt_u32_e32 vcc, 35, v201
	s_nop 1
	v_cndmask_b32_e32 v202, v202, v206, vcc
	v_cndmask_b32_e32 v203, v203, v207, vcc
	v_mov_b32_e32 v212, 0x2000
	v_cndmask_b32_e32 v204, v204, v212, vcc
	s_bfe_u32 s98, s27, 0x40003
	s_bitcmp1_b32 s98, 0
	s_cbranch_scc0 .Lpf_even_p9
	v_mov_b32_e32 v208, v209
.Lpf_even_p9:
	s_branch .LBB0_694
.LBB0_693:
	s_add_i32 s39, s38, 3
	s_cmpk_lt_u32 s38, 0x7d
	s_mov_b32 s38, s39
	s_cbranch_scc0 .LBB0_707
.LBB0_694:
	s_min_u32 s39, s38, 0x7d
	s_add_i32 s39, s39, 2
	s_lshl_b32 s40, s39, 6
	s_add_i32 s40, s40, s37
	v_mad_i64_i32 v[2:3], s[40:41], s40, v194, v[144:145]
	s_waitcnt vmcnt(8)
	v_add_co_u32_e32 v80, vcc, s18, v2
	s_waitcnt lgkmcnt(0)
	s_barrier
	s_nop 0
	v_addc_co_u32_e32 v81, vcc, 0, v3, vcc
	global_load_dwordx4 v[140:143], v[2:3], off
	global_load_dwordx4 v[136:139], v[80:81], off offset:256
	v_add_co_u32_e32 v80, vcc, s19, v2
	s_nop 1
	v_addc_co_u32_e32 v81, vcc, 0, v3, vcc
	v_add_co_u32_e32 v82, vcc, s20, v2
	s_nop 1
	v_addc_co_u32_e32 v83, vcc, 0, v3, vcc
	global_load_dwordx4 v[124:127], v[80:81], off offset:512
	global_load_dwordx4 v[120:123], v[82:83], off offset:768
	v_add_co_u32_e32 v80, vcc, s21, v2
	s_nop 1
	v_addc_co_u32_e32 v81, vcc, 0, v3, vcc
	v_add_co_u32_e32 v82, vcc, 0x3c000, v2
	s_nop 1
	v_addc_co_u32_e32 v83, vcc, 0, v3, vcc
	global_load_dwordx4 v[96:99], v[80:81], off offset:1024
	global_load_dwordx4 v[88:91], v[82:83], off offset:1280
	v_add_co_u32_e32 v80, vcc, 0x48000, v2
	s_nop 1
	v_addc_co_u32_e32 v81, vcc, 0, v3, vcc
	v_add_co_u32_e32 v2, vcc, 0x54000, v2
	s_nop 1
	v_addc_co_u32_e32 v3, vcc, 0, v3, vcc
	global_load_dwordx4 v[84:87], v[80:81], off offset:1536
	s_nop 0
	global_load_dwordx4 v[80:83], v[2:3], off offset:1792
	s_and_b64 vcc, exec, s[6:7]
	s_cbranch_vccnz .LBB0_696
	s_lshl_b32 s39, s39, 3
	s_add_i32 s40, s39, s10
	s_ashr_i32 s41, s40, 31
	s_lshl_b64 s[40:41], s[40:41], 10
	v_lshl_add_u64 v[2:3], v[146:147], 0, s[40:41]
	global_load_dwordx4 v[76:79], v[2:3], off
	s_min_u32 s99, s38, 0x7d
	s_add_i32 s99, s99, 4
	s_min_u32 s99, s99, 0x7f
	v_mad_u64_u32 v[206:207], vcc, v204, s99, v[202:203]
	global_load_dword v205, v[206:207], off
	s_lshl_b32 s99, s99, 6
	s_add_i32 s99, s99, s37
	s_mul_hi_u32 s101, s99, 0x6080
	s_mul_i32 s100, s99, 0x6080
	s_add_u32 s100, s100, s56
	s_addc_u32 s101, s101, s57
	global_load_dword v205, v208, s[100:101]

.LBB0_698:
	s_min_u32 s43, s38, 0x7c
	s_add_i32 s43, s43, 3
	s_lshl_b32 s44, s43, 6
	s_add_i32 s44, s44, s37
	v_mad_i64_i32 v[16:17], s[44:45], s44, v194, v[144:145]
	v_add_co_u32_e32 v18, vcc, 0xc000, v16
	s_waitcnt lgkmcnt(0)
	s_barrier
	s_nop 0
	v_addc_co_u32_e32 v19, vcc, 0, v17, vcc
	global_load_dwordx4 v[48:51], v[16:17], off
	global_load_dwordx4 v[52:55], v[18:19], off offset:256
	v_add_co_u32_e32 v18, vcc, 0x18000, v16
	s_nop 1
	v_addc_co_u32_e32 v19, vcc, 0, v17, vcc
	v_add_co_u32_e32 v20, vcc, 0x24000, v16
	s_nop 1
	v_addc_co_u32_e32 v21, vcc, 0, v17, vcc
	global_load_dwordx4 v[40:43], v[18:19], off offset:512
	global_load_dwordx4 v[44:47], v[20:21], off offset:768
	v_add_co_u32_e32 v18, vcc, 0x30000, v16
	s_nop 1
	v_addc_co_u32_e32 v19, vcc, 0, v17, vcc
	v_add_co_u32_e32 v20, vcc, 0x3c000, v16
	s_nop 1
	v_addc_co_u32_e32 v21, vcc, 0, v17, vcc
	global_load_dwordx4 v[28:31], v[18:19], off offset:1024
	global_load_dwordx4 v[32:35], v[20:21], off offset:1280
	v_add_co_u32_e32 v18, vcc, 0x48000, v16
	s_nop 1
	v_addc_co_u32_e32 v19, vcc, 0, v17, vcc
	v_add_co_u32_e32 v20, vcc, 0x54000, v16
	s_nop 1
	v_addc_co_u32_e32 v21, vcc, 0, v17, vcc
	global_load_dwordx4 v[16:19], v[18:19], off offset:1536
	s_nop 0
	global_load_dwordx4 v[20:23], v[20:21], off offset:1792
	s_and_b64 vcc, exec, s[6:7]
	s_cbranch_vccnz .LBB0_700
	s_lshl_b32 s43, s43, 3
	s_add_i32 s44, s43, s10
	s_ashr_i32 s45, s44, 31
	s_lshl_b64 s[44:45], s[44:45], 10
	v_lshl_add_u64 v[4:5], v[146:147], 0, s[44:45]
	global_load_dwordx4 v[4:7], v[4:5], off
	s_min_u32 s99, s38, 0x7c
	s_add_i32 s99, s99, 5
	s_min_u32 s99, s99, 0x7f
	v_mad_u64_u32 v[206:207], vcc, v204, s99, v[202:203]
	global_load_dword v205, v[206:207], off
	s_lshl_b32 s99, s99, 6
	s_add_i32 s99, s99, s37
	s_mul_hi_u32 s101, s99, 0x6080
	s_mul_i32 s100, s99, 0x6080
	s_add_u32 s100, s100, s56
	s_addc_u32 s101, s101, s57
	global_load_dword v205, v208, s[100:101]

.LBB0_702:
	s_cmpk_gt_u32 s38, 0x7d
	s_cbranch_scc1 .LBB0_693
	s_min_u32 s40, s38, 0x7b
	s_add_i32 s40, s40, 4
	s_lshl_b32 s41, s40, 6
	s_add_i32 s41, s41, s37
	v_mad_i64_i32 v[68:69], s[42:43], s41, v194, v[144:145]
	v_add_co_u32_e32 v12, vcc, 0xc000, v68
	s_waitcnt lgkmcnt(0)
	s_barrier
	s_nop 0
	v_addc_co_u32_e32 v13, vcc, 0, v69, vcc
	v_add_co_u32_e32 v24, vcc, 0x18000, v68
	global_load_dwordx4 v[8:11], v[68:69], off
	s_nop 0
	global_load_dwordx4 v[12:15], v[12:13], off offset:256
	v_addc_co_u32_e32 v25, vcc, 0, v69, vcc
	v_add_co_u32_e32 v36, vcc, 0x24000, v68
	s_nop 1
	v_addc_co_u32_e32 v37, vcc, 0, v69, vcc
	v_add_co_u32_e32 v56, vcc, 0x30000, v68
	global_load_dwordx4 v[24:27], v[24:25], off offset:512
	s_nop 0
	global_load_dwordx4 v[36:39], v[36:37], off offset:768
	v_addc_co_u32_e32 v57, vcc, 0, v69, vcc
	v_add_co_u32_e32 v64, vcc, 0x3c000, v68
	s_nop 1
	v_addc_co_u32_e32 v65, vcc, 0, v69, vcc
	v_add_co_u32_e32 v70, vcc, 0x48000, v68
	global_load_dwordx4 v[56:59], v[56:57], off offset:1024
	s_nop 0
	global_load_dwordx4 v[64:67], v[64:65], off offset:1280
	v_addc_co_u32_e32 v71, vcc, 0, v69, vcc
	v_add_co_u32_e32 v72, vcc, 0x54000, v68
	s_nop 1
	v_addc_co_u32_e32 v73, vcc, 0, v69, vcc
	global_load_dwordx4 v[68:71], v[70:71], off offset:1536
	s_nop 0
	global_load_dwordx4 v[72:75], v[72:73], off offset:1792
	s_and_b64 vcc, exec, s[6:7]
	s_cbranch_vccnz .LBB0_705
	s_lshl_b32 s40, s40, 3
	s_add_i32 s40, s40, s10
	s_ashr_i32 s41, s40, 31
	s_lshl_b64 s[40:41], s[40:41], 10
	v_lshl_add_u64 v[60:61], v[146:147], 0, s[40:41]
	global_load_dwordx4 v[60:63], v[60:61], off
	s_min_u32 s99, s38, 0x7b
	s_add_i32 s99, s99, 6
	s_min_u32 s99, s99, 0x7f
	v_mad_u64_u32 v[206:207], vcc, v204, s99, v[202:203]
	global_load_dword v205, v[206:207], off
	s_lshl_b32 s99, s99, 6
	s_add_i32 s99, s99, s37
	s_mul_hi_u32 s101, s99, 0x6080
	s_mul_i32 s100, s99, 0x6080
	s_add_u32 s100, s100, s56
	s_addc_u32 s101, s101, s57
	global_load_dword v205, v208, s[100:101]
